# gate-GEMM merge epilogue rewritten by hand on packed f32 ops (bias and -log2e folded into v_pk_fma, in-place accumulation)
# speedup vs baseline: 1.0100x; 1.0087x over previous
; __device__ __forceinline__ float bf2f(unsigned b) { return __uint_as_float(b << 16); }
; __device__ __forceinline__ unsigned cvt_pk_bf16(float lo, float hi) { unsigned r; asm volatile("v_cvt_pk_bf16_f32 %0, %1, %2" : "=v"(r) : "v"(lo), "v"(hi)); return r; }
; __device__ __forceinline__ float sigmoid_fast(float x) { return __builtin_amdgcn_rcpf(1.0f + __expf(-x)); }
;     __device__ __forceinline__ void operator()(EPI_SIG) const {
;         const int row0 = u.pm * 256 + wr * 64 + fr, oc = u.pn * 64 + wc * 16 + 4 * fq;
;         f32x4 bv[4];
; #pragma unroll
;         for (int g = 0; g < 4; ++g) bv[g] = *(const f32x4*)(bg + g * 1024 + oc);
; #pragma unroll
;         for (int ai = 0; ai < 2; ++ai)
; #pragma unroll
;             for (int m = 0; m < 4; ++m) { const int row = row0 + ai * 128 + m * 16; const bf16* prow = P + (((((size_t)u.pm * 16 + u.pn) * 2 + ai) * 4 + m) * 8 + (wr * 4 + wc)) * 1024 + (fq * 16 + fr) * 4;
;                 v2u pw[4];
; #pragma unroll
;                 for (int g = 0; g < 4; ++g) pw[g] = *(const v2u*)(prow + g * 256);
;                 f32x4 t = (f32x4){0.f, 0.f, 0.f, 0.f};
; #pragma unroll
;                 for (int bj = 0; bj < 2; ++bj)
; #pragma unroll
;                     for (int n = 0; n < 2; ++n) { const int g = 2 * bj + n; const f32x4 a = acc[ai][bj][m][n] + bv[g];
;                         t[0] += sigmoid_fast(a[0]) * bf2f(pw[g].x & 0xffffu); t[1] += sigmoid_fast(a[1]) * bf2f(pw[g].x >> 16);
;                         t[2] += sigmoid_fast(a[2]) * bf2f(pw[g].y & 0xffffu); t[3] += sigmoid_fast(a[3]) * bf2f(pw[g].y >> 16); }
;                 v2u w; w.x = cvt_pk_bf16(t[0], t[1]); w.y = cvt_pk_bf16(t[2], t[3]);
;                 *(v2u*)(T + (size_t)row * 1024 + oc) = w; }
.LBB0_1859:
	v_lshl_or_b32 v18, s44, 6, v190
	v_ashrrev_i32_e32 v19, 31, v18
	s_nop 7
	s_nop 7
	s_nop 3
	v_lshl_add_u64 v[2:3], v[18:19], 2, s[8:9]
	global_load_dwordx4 v[14:17], v[2:3], off
	v_add_co_u32_e32 v4, vcc, 0x1000, v2
	s_ashr_i32 s47, s46, 31
	s_nop 0
	v_addc_co_u32_e32 v5, vcc, 0, v3, vcc
	global_load_dwordx4 v[10:13], v[4:5], off
	s_ashr_i32 s45, s44, 31
	v_add_co_u32_e32 v4, vcc, 0x2000, v2
	s_lshl_b64 s[2:3], s[46:47], 21
	s_lshl_b64 s[14:15], s[44:45], 17
	v_addc_co_u32_e32 v5, vcc, 0, v3, vcc
	s_add_u32 s44, s2, s14
	v_add_co_u32_e32 v2, vcc, 0x3000, v2
	s_addc_u32 s45, s3, s15
	s_nop 0
	v_addc_co_u32_e32 v3, vcc, 0, v3, vcc
	v_lshl_add_u64 v[24:25], v[168:169], 0, s[44:45]
	global_load_dwordx4 v[6:9], v[4:5], off
	v_lshl_add_u32 v20, s46, 8, v50
	global_load_dwordx4 v[2:5], v[2:3], off
	s_nop 0
	global_load_dwordx2 v[26:27], v[24:25], off nt
	global_load_dwordx2 v[28:29], v[24:25], off offset:512 nt
	global_load_dwordx2 v[22:23], v[24:25], off offset:1024 nt
	s_nop 0
	global_load_dwordx2 v[24:25], v[24:25], off offset:1536 nt
	s_add_u32 s14, s44, 0x10000
	s_addc_u32 s15, s45, 0
	v_lshl_add_u64 v[206:207], v[170:171], 0, s[44:45]
	global_load_dwordx2 v[200:201], v[206:207], off nt
	global_load_dwordx2 v[202:203], v[206:207], off offset:512 nt
	global_load_dwordx2 v[204:205], v[206:207], off offset:1024 nt
	s_nop 0
	global_load_dwordx2 v[206:207], v[206:207], off offset:1536 nt
	v_lshl_add_u64 v[214:215], v[172:173], 0, s[44:45]
	global_load_dwordx2 v[208:209], v[214:215], off nt
	global_load_dwordx2 v[210:211], v[214:215], off offset:512 nt
	global_load_dwordx2 v[212:213], v[214:215], off offset:1024 nt
	s_nop 0
	global_load_dwordx2 v[214:215], v[214:215], off offset:1536 nt
	v_lshl_add_u64 v[222:223], v[174:175], 0, s[44:45]
	global_load_dwordx2 v[216:217], v[222:223], off nt
	global_load_dwordx2 v[218:219], v[222:223], off offset:512 nt
	global_load_dwordx2 v[220:221], v[222:223], off offset:1024 nt
	s_nop 0
	global_load_dwordx2 v[222:223], v[222:223], off offset:1536 nt
	v_lshl_add_u64 v[248:249], v[168:169], 0, s[14:15]
	global_load_dwordx2 v[242:243], v[248:249], off nt
	global_load_dwordx2 v[244:245], v[248:249], off offset:512 nt
	global_load_dwordx2 v[246:247], v[248:249], off offset:1024 nt
	s_nop 0
	global_load_dwordx2 v[248:249], v[248:249], off offset:1536 nt
	s_mov_b32 s58, 0x3f6c835e
	s_mov_b32 s59, 0xbec3ef15
	v_mov_b32_e32 v180, 0xbfb8aa3b
	v_mov_b32_e32 v181, 0xbfb8aa3b
	v_mov_b32_e32 v182, 1.0
	v_mov_b32_e32 v183, 1.0
	v_ashrrev_i32_e32 v21, 31, v20
	v_lshlrev_b64 v[20:21], 11, v[20:21]
	v_lshlrev_b64 v[18:19], 1, v[18:19]
	v_lshl_add_u64 v[20:21], s[6:7], 0, v[20:21]
	v_lshl_add_u64 v[20:21], v[20:21], 0, v[18:19]
	s_mov_b64 s[2:3], 0x8000
	s_waitcnt vmcnt(16)
	v_pk_mul_f32 v[2:3], v[2:3], v[180:181]
	v_pk_mul_f32 v[4:5], v[4:5], v[180:181]
	v_pk_mul_f32 v[6:7], v[6:7], v[180:181]
	v_pk_mul_f32 v[8:9], v[8:9], v[180:181]
	v_pk_mul_f32 v[10:11], v[10:11], v[180:181]
	v_pk_mul_f32 v[12:13], v[12:13], v[180:181]
	v_pk_mul_f32 v[14:15], v[14:15], v[180:181]
	v_pk_mul_f32 v[16:17], v[16:17], v[180:181]
	v_pk_fma_f32 v[160:161], v[160:161], v[180:181], v[14:15]
	v_pk_fma_f32 v[162:163], v[162:163], v[180:181], v[16:17]
	v_exp_f32_e32 v160, v160
	v_exp_f32_e32 v162, v162
	v_exp_f32_e32 v161, v161
	v_exp_f32_e32 v163, v163
	v_lshlrev_b32_e32 v184, 16, v26
	v_pk_add_f32 v[160:161], v[160:161], v[182:183]
	v_pk_add_f32 v[162:163], v[162:163], v[182:183]
	v_rcp_f32_e32 v160, v160
	v_rcp_f32_e32 v162, v162
	v_rcp_f32_e32 v161, v161
	v_rcp_f32_e32 v163, v163
	v_and_b32_e32 v185, 0xffff0000, v26
	v_lshlrev_b32_e32 v186, 16, v27
	v_and_b32_e32 v187, 0xffff0000, v27
	v_pk_mul_f32 v[160:161], v[160:161], v[184:185]
	v_pk_mul_f32 v[162:163], v[162:163], v[186:187]
	v_pk_fma_f32 v[156:157], v[156:157], v[180:181], v[10:11]
	v_pk_fma_f32 v[158:159], v[158:159], v[180:181], v[12:13]
	v_exp_f32_e32 v156, v156
	v_exp_f32_e32 v158, v158
	v_exp_f32_e32 v157, v157
	v_exp_f32_e32 v159, v159
	v_lshlrev_b32_e32 v184, 16, v28
	v_pk_add_f32 v[156:157], v[156:157], v[182:183]
	v_pk_add_f32 v[158:159], v[158:159], v[182:183]
	v_rcp_f32_e32 v156, v156
	v_rcp_f32_e32 v158, v158
	v_rcp_f32_e32 v157, v157
	v_rcp_f32_e32 v159, v159
	v_and_b32_e32 v185, 0xffff0000, v28
	v_lshlrev_b32_e32 v186, 16, v29
	v_and_b32_e32 v187, 0xffff0000, v29
	v_pk_fma_f32 v[160:161], v[156:157], v[184:185], v[160:161]
	v_pk_fma_f32 v[162:163], v[158:159], v[186:187], v[162:163]
	v_pk_fma_f32 v[152:153], v[152:153], v[180:181], v[6:7]
	v_pk_fma_f32 v[154:155], v[154:155], v[180:181], v[8:9]
	v_exp_f32_e32 v152, v152
	v_exp_f32_e32 v154, v154
	v_exp_f32_e32 v153, v153
	v_exp_f32_e32 v155, v155
	v_lshlrev_b32_e32 v184, 16, v22
	v_pk_add_f32 v[152:153], v[152:153], v[182:183]
	v_pk_add_f32 v[154:155], v[154:155], v[182:183]
	v_rcp_f32_e32 v152, v152
	v_rcp_f32_e32 v154, v154
	v_rcp_f32_e32 v153, v153
	v_rcp_f32_e32 v155, v155
	v_and_b32_e32 v185, 0xffff0000, v22
	v_lshlrev_b32_e32 v186, 16, v23
	v_and_b32_e32 v187, 0xffff0000, v23
	v_pk_fma_f32 v[160:161], v[152:153], v[184:185], v[160:161]
	v_pk_fma_f32 v[162:163], v[154:155], v[186:187], v[162:163]
	v_pk_fma_f32 v[148:149], v[148:149], v[180:181], v[2:3]
	v_pk_fma_f32 v[150:151], v[150:151], v[180:181], v[4:5]
	v_exp_f32_e32 v148, v148
	v_exp_f32_e32 v150, v150
	v_exp_f32_e32 v149, v149
	v_exp_f32_e32 v151, v151
	v_lshlrev_b32_e32 v184, 16, v24
	v_pk_add_f32 v[148:149], v[148:149], v[182:183]
	v_pk_add_f32 v[150:151], v[150:151], v[182:183]
	v_rcp_f32_e32 v148, v148
	v_rcp_f32_e32 v150, v150
	v_rcp_f32_e32 v149, v149
	v_rcp_f32_e32 v151, v151
	v_and_b32_e32 v185, 0xffff0000, v24
	v_lshlrev_b32_e32 v186, 16, v25
	v_and_b32_e32 v187, 0xffff0000, v25
	v_pk_fma_f32 v[160:161], v[148:149], v[184:185], v[160:161]
	v_pk_fma_f32 v[162:163], v[150:151], v[186:187], v[162:163]
	v_cvt_pk_bf16_f32 v18, v160, v161
	v_cvt_pk_bf16_f32 v19, v162, v163
	global_store_dwordx2 v[20:21], v[18:19], off
	s_nop 1
	v_lshl_add_u64 v[20:21], v[20:21], 0, s[2:3]
	s_waitcnt vmcnt(12)
; __device__ __forceinline__ float bf2f(unsigned b) { return __uint_as_float(b << 16); }
; __device__ __forceinline__ unsigned cvt_pk_bf16(float lo, float hi) { unsigned r; asm volatile("v_cvt_pk_bf16_f32 %0, %1, %2" : "=v"(r) : "v"(lo), "v"(hi)); return r; }
; __device__ __forceinline__ float sigmoid_fast(float x) { return __builtin_amdgcn_rcpf(1.0f + __expf(-x)); }
;     __device__ __forceinline__ void operator()(EPI_SIG) const {
;     ...
;             for (int m = 0; m < 4; ++m) { const int row = row0 + ai * 128 + m * 16; const bf16* prow = P + (((((size_t)u.pm * 16 + u.pn) * 2 + ai) * 4 + m) * 8 + (wr * 4 + wc)) * 1024 + (fq * 16 + fr) * 4;
;                 v2u pw[4];
; #pragma unroll
;                 for (int g = 0; g < 4; ++g) pw[g] = *(const v2u*)(prow + g * 256);
;                 f32x4 t = (f32x4){0.f, 0.f, 0.f, 0.f};
; #pragma unroll
;                 for (int bj = 0; bj < 2; ++bj)
; #pragma unroll
;                     for (int n = 0; n < 2; ++n) { const int g = 2 * bj + n; const f32x4 a = acc[ai][bj][m][n] + bv[g];
;                         t[0] += sigmoid_fast(a[0]) * bf2f(pw[g].x & 0xffffu); t[1] += sigmoid_fast(a[1]) * bf2f(pw[g].x >> 16);
;                         t[2] += sigmoid_fast(a[2]) * bf2f(pw[g].y & 0xffffu); t[3] += sigmoid_fast(a[3]) * bf2f(pw[g].y >> 16); }
;                 v2u w; w.x = cvt_pk_bf16(t[0], t[1]); w.y = cvt_pk_bf16(t[2], t[3]);
;                 *(v2u*)(T + (size_t)row * 1024 + oc) = w; }
	v_pk_fma_f32 v[144:145], v[144:145], v[180:181], v[14:15]
	v_pk_fma_f32 v[146:147], v[146:147], v[180:181], v[16:17]
	v_exp_f32_e32 v144, v144
	v_exp_f32_e32 v146, v146
	v_exp_f32_e32 v145, v145
	v_exp_f32_e32 v147, v147
	v_lshlrev_b32_e32 v184, 16, v200
	v_pk_add_f32 v[144:145], v[144:145], v[182:183]
	v_pk_add_f32 v[146:147], v[146:147], v[182:183]
	v_rcp_f32_e32 v144, v144
	v_rcp_f32_e32 v146, v146
	v_rcp_f32_e32 v145, v145
	v_rcp_f32_e32 v147, v147
	v_and_b32_e32 v185, 0xffff0000, v200
	v_lshlrev_b32_e32 v186, 16, v201
	v_and_b32_e32 v187, 0xffff0000, v201
	v_pk_mul_f32 v[144:145], v[144:145], v[184:185]
	v_pk_mul_f32 v[146:147], v[146:147], v[186:187]
	v_pk_fma_f32 v[140:141], v[140:141], v[180:181], v[10:11]
	v_pk_fma_f32 v[142:143], v[142:143], v[180:181], v[12:13]
	v_exp_f32_e32 v140, v140
	v_exp_f32_e32 v142, v142
	v_exp_f32_e32 v141, v141
	v_exp_f32_e32 v143, v143
	v_lshlrev_b32_e32 v184, 16, v202
	v_pk_add_f32 v[140:141], v[140:141], v[182:183]
	v_pk_add_f32 v[142:143], v[142:143], v[182:183]
	v_rcp_f32_e32 v140, v140
	v_rcp_f32_e32 v142, v142
	v_rcp_f32_e32 v141, v141
	v_rcp_f32_e32 v143, v143
	v_and_b32_e32 v185, 0xffff0000, v202
	v_lshlrev_b32_e32 v186, 16, v203
	v_and_b32_e32 v187, 0xffff0000, v203
	v_pk_fma_f32 v[144:145], v[140:141], v[184:185], v[144:145]
	v_pk_fma_f32 v[146:147], v[142:143], v[186:187], v[146:147]
	v_pk_fma_f32 v[136:137], v[136:137], v[180:181], v[6:7]
	v_pk_fma_f32 v[138:139], v[138:139], v[180:181], v[8:9]
	v_exp_f32_e32 v136, v136
	v_exp_f32_e32 v138, v138
	v_exp_f32_e32 v137, v137
	v_exp_f32_e32 v139, v139
	v_lshlrev_b32_e32 v184, 16, v204
	v_pk_add_f32 v[136:137], v[136:137], v[182:183]
	v_pk_add_f32 v[138:139], v[138:139], v[182:183]
	v_rcp_f32_e32 v136, v136
	v_rcp_f32_e32 v138, v138
	v_rcp_f32_e32 v137, v137
	v_rcp_f32_e32 v139, v139
	v_and_b32_e32 v185, 0xffff0000, v204
	v_lshlrev_b32_e32 v186, 16, v205
	v_and_b32_e32 v187, 0xffff0000, v205
	v_pk_fma_f32 v[144:145], v[136:137], v[184:185], v[144:145]
	v_pk_fma_f32 v[146:147], v[138:139], v[186:187], v[146:147]
	v_pk_fma_f32 v[132:133], v[132:133], v[180:181], v[2:3]
	v_pk_fma_f32 v[134:135], v[134:135], v[180:181], v[4:5]
	v_exp_f32_e32 v132, v132
	v_exp_f32_e32 v134, v134
	v_exp_f32_e32 v133, v133
	v_exp_f32_e32 v135, v135
	v_lshlrev_b32_e32 v184, 16, v206
	v_pk_add_f32 v[132:133], v[132:133], v[182:183]
	v_pk_add_f32 v[134:135], v[134:135], v[182:183]
	v_rcp_f32_e32 v132, v132
	v_rcp_f32_e32 v134, v134
	v_rcp_f32_e32 v133, v133
	v_rcp_f32_e32 v135, v135
	v_and_b32_e32 v185, 0xffff0000, v206
	v_lshlrev_b32_e32 v186, 16, v207
	v_and_b32_e32 v187, 0xffff0000, v207
	v_pk_fma_f32 v[144:145], v[132:133], v[184:185], v[144:145]
	v_pk_fma_f32 v[146:147], v[134:135], v[186:187], v[146:147]
	v_cvt_pk_bf16_f32 v18, v144, v145
	v_cvt_pk_bf16_f32 v19, v146, v147
	global_store_dwordx2 v[20:21], v[18:19], off
	s_nop 1
	v_lshl_add_u64 v[206:207], v[170:171], 0, s[14:15]
	global_load_dwordx2 v[200:201], v[206:207], off nt
	global_load_dwordx2 v[202:203], v[206:207], off offset:512 nt
	global_load_dwordx2 v[204:205], v[206:207], off offset:1024 nt
	s_nop 0
	global_load_dwordx2 v[206:207], v[206:207], off offset:1536 nt
	v_lshl_add_u64 v[20:21], v[20:21], 0, s[2:3]
	s_waitcnt vmcnt(12)
	v_pk_fma_f32 v[128:129], v[128:129], v[180:181], v[14:15]
	v_pk_fma_f32 v[130:131], v[130:131], v[180:181], v[16:17]
	v_exp_f32_e32 v128, v128
	v_exp_f32_e32 v130, v130
	v_exp_f32_e32 v129, v129
	v_exp_f32_e32 v131, v131
	v_lshlrev_b32_e32 v184, 16, v208
	v_pk_add_f32 v[128:129], v[128:129], v[182:183]
	v_pk_add_f32 v[130:131], v[130:131], v[182:183]
	v_rcp_f32_e32 v128, v128
	v_rcp_f32_e32 v130, v130
	v_rcp_f32_e32 v129, v129
	v_rcp_f32_e32 v131, v131
	v_and_b32_e32 v185, 0xffff0000, v208
	v_lshlrev_b32_e32 v186, 16, v209
	v_and_b32_e32 v187, 0xffff0000, v209
	v_pk_mul_f32 v[128:129], v[128:129], v[184:185]
	v_pk_mul_f32 v[130:131], v[130:131], v[186:187]
	v_pk_fma_f32 v[124:125], v[124:125], v[180:181], v[10:11]
	v_pk_fma_f32 v[126:127], v[126:127], v[180:181], v[12:13]
	v_exp_f32_e32 v124, v124
	v_exp_f32_e32 v126, v126
	v_exp_f32_e32 v125, v125
	v_exp_f32_e32 v127, v127
	v_lshlrev_b32_e32 v184, 16, v210
	v_pk_add_f32 v[124:125], v[124:125], v[182:183]
	v_pk_add_f32 v[126:127], v[126:127], v[182:183]
	v_rcp_f32_e32 v124, v124
	v_rcp_f32_e32 v126, v126
	v_rcp_f32_e32 v125, v125
	v_rcp_f32_e32 v127, v127
	v_and_b32_e32 v185, 0xffff0000, v210
	v_lshlrev_b32_e32 v186, 16, v211
	v_and_b32_e32 v187, 0xffff0000, v211
	v_pk_fma_f32 v[128:129], v[124:125], v[184:185], v[128:129]
	v_pk_fma_f32 v[130:131], v[126:127], v[186:187], v[130:131]
	v_pk_fma_f32 v[120:121], v[120:121], v[180:181], v[6:7]
	v_pk_fma_f32 v[122:123], v[122:123], v[180:181], v[8:9]
	v_exp_f32_e32 v120, v120
	v_exp_f32_e32 v122, v122
	v_exp_f32_e32 v121, v121
	v_exp_f32_e32 v123, v123
	v_lshlrev_b32_e32 v184, 16, v212
	v_pk_add_f32 v[120:121], v[120:121], v[182:183]
	v_pk_add_f32 v[122:123], v[122:123], v[182:183]
	v_rcp_f32_e32 v120, v120
	v_rcp_f32_e32 v122, v122
	v_rcp_f32_e32 v121, v121
	v_rcp_f32_e32 v123, v123
	v_and_b32_e32 v185, 0xffff0000, v212
	v_lshlrev_b32_e32 v186, 16, v213
	v_and_b32_e32 v187, 0xffff0000, v213
	v_pk_fma_f32 v[128:129], v[120:121], v[184:185], v[128:129]
	v_pk_fma_f32 v[130:131], v[122:123], v[186:187], v[130:131]
	v_pk_fma_f32 v[116:117], v[116:117], v[180:181], v[2:3]
	v_pk_fma_f32 v[118:119], v[118:119], v[180:181], v[4:5]
	v_exp_f32_e32 v116, v116
	v_exp_f32_e32 v118, v118
	v_exp_f32_e32 v117, v117
	v_exp_f32_e32 v119, v119
	v_lshlrev_b32_e32 v184, 16, v214
	v_pk_add_f32 v[116:117], v[116:117], v[182:183]
	v_pk_add_f32 v[118:119], v[118:119], v[182:183]
	v_rcp_f32_e32 v116, v116
	v_rcp_f32_e32 v118, v118
	v_rcp_f32_e32 v117, v117
	v_rcp_f32_e32 v119, v119
	v_and_b32_e32 v185, 0xffff0000, v214
	v_lshlrev_b32_e32 v186, 16, v215
	v_and_b32_e32 v187, 0xffff0000, v215
	v_pk_fma_f32 v[128:129], v[116:117], v[184:185], v[128:129]
	v_pk_fma_f32 v[130:131], v[118:119], v[186:187], v[130:131]
	v_cvt_pk_bf16_f32 v18, v128, v129
	v_cvt_pk_bf16_f32 v19, v130, v131
	global_store_dwordx2 v[20:21], v[18:19], off
	s_nop 1
	v_lshl_add_u64 v[214:215], v[172:173], 0, s[14:15]
	global_load_dwordx2 v[208:209], v[214:215], off nt
	global_load_dwordx2 v[210:211], v[214:215], off offset:512 nt
	global_load_dwordx2 v[212:213], v[214:215], off offset:1024 nt
	s_nop 0
	global_load_dwordx2 v[214:215], v[214:215], off offset:1536 nt
	v_lshl_add_u64 v[20:21], v[20:21], 0, s[2:3]
	s_waitcnt vmcnt(12)
; __device__ __forceinline__ float bf2f(unsigned b) { return __uint_as_float(b << 16); }
; __device__ __forceinline__ unsigned cvt_pk_bf16(float lo, float hi) { unsigned r; asm volatile("v_cvt_pk_bf16_f32 %0, %1, %2" : "=v"(r) : "v"(lo), "v"(hi)); return r; }
; __device__ __forceinline__ float sigmoid_fast(float x) { return __builtin_amdgcn_rcpf(1.0f + __expf(-x)); }
;     __device__ __forceinline__ void operator()(EPI_SIG) const {
;     ...
;             for (int m = 0; m < 4; ++m) { const int row = row0 + ai * 128 + m * 16; const bf16* prow = P + (((((size_t)u.pm * 16 + u.pn) * 2 + ai) * 4 + m) * 8 + (wr * 4 + wc)) * 1024 + (fq * 16 + fr) * 4;
;                 v2u pw[4];
; #pragma unroll
;                 for (int g = 0; g < 4; ++g) pw[g] = *(const v2u*)(prow + g * 256);
;                 f32x4 t = (f32x4){0.f, 0.f, 0.f, 0.f};
; #pragma unroll
;                 for (int bj = 0; bj < 2; ++bj)
; #pragma unroll
;                     for (int n = 0; n < 2; ++n) { const int g = 2 * bj + n; const f32x4 a = acc[ai][bj][m][n] + bv[g];
;                         t[0] += sigmoid_fast(a[0]) * bf2f(pw[g].x & 0xffffu); t[1] += sigmoid_fast(a[1]) * bf2f(pw[g].x >> 16);
;                         t[2] += sigmoid_fast(a[2]) * bf2f(pw[g].y & 0xffffu); t[3] += sigmoid_fast(a[3]) * bf2f(pw[g].y >> 16); }
;                 v2u w; w.x = cvt_pk_bf16(t[0], t[1]); w.y = cvt_pk_bf16(t[2], t[3]);
;                 *(v2u*)(T + (size_t)row * 1024 + oc) = w; }
	v_pk_fma_f32 v[112:113], v[112:113], v[180:181], v[14:15]
	v_pk_fma_f32 v[114:115], v[114:115], v[180:181], v[16:17]
	v_exp_f32_e32 v112, v112
	v_exp_f32_e32 v114, v114
	v_exp_f32_e32 v113, v113
	v_exp_f32_e32 v115, v115
	v_lshlrev_b32_e32 v184, 16, v216
	v_pk_add_f32 v[112:113], v[112:113], v[182:183]
	v_pk_add_f32 v[114:115], v[114:115], v[182:183]
	v_rcp_f32_e32 v112, v112
	v_rcp_f32_e32 v114, v114
	v_rcp_f32_e32 v113, v113
	v_rcp_f32_e32 v115, v115
	v_and_b32_e32 v185, 0xffff0000, v216
	v_lshlrev_b32_e32 v186, 16, v217
	v_and_b32_e32 v187, 0xffff0000, v217
	v_pk_mul_f32 v[112:113], v[112:113], v[184:185]
	v_pk_mul_f32 v[114:115], v[114:115], v[186:187]
	v_pk_fma_f32 v[108:109], v[108:109], v[180:181], v[10:11]
	v_pk_fma_f32 v[110:111], v[110:111], v[180:181], v[12:13]
	v_exp_f32_e32 v108, v108
	v_exp_f32_e32 v110, v110
	v_exp_f32_e32 v109, v109
	v_exp_f32_e32 v111, v111
	v_lshlrev_b32_e32 v184, 16, v218
	v_pk_add_f32 v[108:109], v[108:109], v[182:183]
	v_pk_add_f32 v[110:111], v[110:111], v[182:183]
	v_rcp_f32_e32 v108, v108
	v_rcp_f32_e32 v110, v110
	v_rcp_f32_e32 v109, v109
	v_rcp_f32_e32 v111, v111
	v_and_b32_e32 v185, 0xffff0000, v218
	v_lshlrev_b32_e32 v186, 16, v219
	v_and_b32_e32 v187, 0xffff0000, v219
	v_pk_fma_f32 v[112:113], v[108:109], v[184:185], v[112:113]
	v_pk_fma_f32 v[114:115], v[110:111], v[186:187], v[114:115]
	v_pk_fma_f32 v[104:105], v[104:105], v[180:181], v[6:7]
	v_pk_fma_f32 v[106:107], v[106:107], v[180:181], v[8:9]
	v_exp_f32_e32 v104, v104
	v_exp_f32_e32 v106, v106
	v_exp_f32_e32 v105, v105
	v_exp_f32_e32 v107, v107
	v_lshlrev_b32_e32 v184, 16, v220
	v_pk_add_f32 v[104:105], v[104:105], v[182:183]
	v_pk_add_f32 v[106:107], v[106:107], v[182:183]
	v_rcp_f32_e32 v104, v104
	v_rcp_f32_e32 v106, v106
	v_rcp_f32_e32 v105, v105
	v_rcp_f32_e32 v107, v107
	v_and_b32_e32 v185, 0xffff0000, v220
	v_lshlrev_b32_e32 v186, 16, v221
	v_and_b32_e32 v187, 0xffff0000, v221
	v_pk_fma_f32 v[112:113], v[104:105], v[184:185], v[112:113]
	v_pk_fma_f32 v[114:115], v[106:107], v[186:187], v[114:115]
	v_pk_fma_f32 v[100:101], v[100:101], v[180:181], v[2:3]
	v_pk_fma_f32 v[102:103], v[102:103], v[180:181], v[4:5]
	v_exp_f32_e32 v100, v100
	v_exp_f32_e32 v102, v102
	v_exp_f32_e32 v101, v101
	v_exp_f32_e32 v103, v103
	v_lshlrev_b32_e32 v184, 16, v222
	v_pk_add_f32 v[100:101], v[100:101], v[182:183]
	v_pk_add_f32 v[102:103], v[102:103], v[182:183]
	v_rcp_f32_e32 v100, v100
	v_rcp_f32_e32 v102, v102
	v_rcp_f32_e32 v101, v101
	v_rcp_f32_e32 v103, v103
	v_and_b32_e32 v185, 0xffff0000, v222
	v_lshlrev_b32_e32 v186, 16, v223
	v_and_b32_e32 v187, 0xffff0000, v223
	v_pk_fma_f32 v[112:113], v[100:101], v[184:185], v[112:113]
	v_pk_fma_f32 v[114:115], v[102:103], v[186:187], v[114:115]
	v_cvt_pk_bf16_f32 v18, v112, v113
	v_cvt_pk_bf16_f32 v19, v114, v115
	global_store_dwordx2 v[20:21], v[18:19], off
	s_nop 1
	v_lshl_add_u64 v[222:223], v[174:175], 0, s[14:15]
	global_load_dwordx2 v[216:217], v[222:223], off nt
	global_load_dwordx2 v[218:219], v[222:223], off offset:512 nt
	global_load_dwordx2 v[220:221], v[222:223], off offset:1024 nt
	s_nop 0
	global_load_dwordx2 v[222:223], v[222:223], off offset:1536 nt
	s_mov_b64 s[14:15], 0x28000
	v_lshl_add_u64 v[20:21], v[20:21], 0, s[14:15]
	s_waitcnt vmcnt(12)
	v_pk_fma_f32 v[96:97], v[96:97], v[180:181], v[14:15]
	v_pk_fma_f32 v[98:99], v[98:99], v[180:181], v[16:17]
	v_exp_f32_e32 v96, v96
	v_exp_f32_e32 v98, v98
	v_exp_f32_e32 v97, v97
	v_exp_f32_e32 v99, v99
	v_lshlrev_b32_e32 v184, 16, v242
	v_pk_add_f32 v[96:97], v[96:97], v[182:183]
	v_pk_add_f32 v[98:99], v[98:99], v[182:183]
	v_rcp_f32_e32 v96, v96
	v_rcp_f32_e32 v98, v98
	v_rcp_f32_e32 v97, v97
	v_rcp_f32_e32 v99, v99
	v_and_b32_e32 v185, 0xffff0000, v242
	v_lshlrev_b32_e32 v186, 16, v243
	v_and_b32_e32 v187, 0xffff0000, v243
	v_pk_mul_f32 v[96:97], v[96:97], v[184:185]
	v_pk_mul_f32 v[98:99], v[98:99], v[186:187]
	v_pk_fma_f32 v[92:93], v[92:93], v[180:181], v[10:11]
	v_pk_fma_f32 v[94:95], v[94:95], v[180:181], v[12:13]
	v_exp_f32_e32 v92, v92
	v_exp_f32_e32 v94, v94
	v_exp_f32_e32 v93, v93
	v_exp_f32_e32 v95, v95
	v_lshlrev_b32_e32 v184, 16, v244
	v_pk_add_f32 v[92:93], v[92:93], v[182:183]
	v_pk_add_f32 v[94:95], v[94:95], v[182:183]
	v_rcp_f32_e32 v92, v92
	v_rcp_f32_e32 v94, v94
	v_rcp_f32_e32 v93, v93
	v_rcp_f32_e32 v95, v95
	v_and_b32_e32 v185, 0xffff0000, v244
	v_lshlrev_b32_e32 v186, 16, v245
	v_and_b32_e32 v187, 0xffff0000, v245
	v_pk_fma_f32 v[96:97], v[92:93], v[184:185], v[96:97]
	v_pk_fma_f32 v[98:99], v[94:95], v[186:187], v[98:99]
	v_pk_fma_f32 v[88:89], v[88:89], v[180:181], v[6:7]
	v_pk_fma_f32 v[90:91], v[90:91], v[180:181], v[8:9]
	v_exp_f32_e32 v88, v88
	v_exp_f32_e32 v90, v90
	v_exp_f32_e32 v89, v89
	v_exp_f32_e32 v91, v91
	v_lshlrev_b32_e32 v184, 16, v246
	v_pk_add_f32 v[88:89], v[88:89], v[182:183]
	v_pk_add_f32 v[90:91], v[90:91], v[182:183]
	v_rcp_f32_e32 v88, v88
	v_rcp_f32_e32 v90, v90
	v_rcp_f32_e32 v89, v89
	v_rcp_f32_e32 v91, v91
	v_and_b32_e32 v185, 0xffff0000, v246
	v_lshlrev_b32_e32 v186, 16, v247
	v_and_b32_e32 v187, 0xffff0000, v247
	v_pk_fma_f32 v[96:97], v[88:89], v[184:185], v[96:97]
	v_pk_fma_f32 v[98:99], v[90:91], v[186:187], v[98:99]
	v_pk_fma_f32 v[84:85], v[84:85], v[180:181], v[2:3]
	v_pk_fma_f32 v[86:87], v[86:87], v[180:181], v[4:5]
	v_exp_f32_e32 v84, v84
	v_exp_f32_e32 v86, v86
	v_exp_f32_e32 v85, v85
	v_exp_f32_e32 v87, v87
	v_lshlrev_b32_e32 v184, 16, v248
	v_pk_add_f32 v[84:85], v[84:85], v[182:183]
	v_pk_add_f32 v[86:87], v[86:87], v[182:183]
	v_rcp_f32_e32 v84, v84
	v_rcp_f32_e32 v86, v86
	v_rcp_f32_e32 v85, v85
	v_rcp_f32_e32 v87, v87
	v_and_b32_e32 v185, 0xffff0000, v248
	v_lshlrev_b32_e32 v186, 16, v249
	v_and_b32_e32 v187, 0xffff0000, v249
	v_pk_fma_f32 v[96:97], v[84:85], v[184:185], v[96:97]
	v_pk_fma_f32 v[98:99], v[86:87], v[186:187], v[98:99]
	v_cvt_pk_bf16_f32 v18, v96, v97
	v_cvt_pk_bf16_f32 v19, v98, v99
	global_store_dwordx2 v[20:21], v[18:19], off
	s_nop 1
	v_lshl_add_u64 v[20:21], v[20:21], 0, s[2:3]
	s_waitcnt vmcnt(8)
; __device__ __forceinline__ float bf2f(unsigned b) { return __uint_as_float(b << 16); }
; __device__ __forceinline__ unsigned cvt_pk_bf16(float lo, float hi) { unsigned r; asm volatile("v_cvt_pk_bf16_f32 %0, %1, %2" : "=v"(r) : "v"(lo), "v"(hi)); return r; }
; __device__ __forceinline__ float sigmoid_fast(float x) { return __builtin_amdgcn_rcpf(1.0f + __expf(-x)); }
;     __device__ __forceinline__ void operator()(EPI_SIG) const {
;     ...
;             for (int m = 0; m < 4; ++m) { const int row = row0 + ai * 128 + m * 16; const bf16* prow = P + (((((size_t)u.pm * 16 + u.pn) * 2 + ai) * 4 + m) * 8 + (wr * 4 + wc)) * 1024 + (fq * 16 + fr) * 4;
;                 v2u pw[4];
; #pragma unroll
;                 for (int g = 0; g < 4; ++g) pw[g] = *(const v2u*)(prow + g * 256);
;                 f32x4 t = (f32x4){0.f, 0.f, 0.f, 0.f};
; #pragma unroll
;                 for (int bj = 0; bj < 2; ++bj)
; #pragma unroll
;                     for (int n = 0; n < 2; ++n) { const int g = 2 * bj + n; const f32x4 a = acc[ai][bj][m][n] + bv[g];
;                         t[0] += sigmoid_fast(a[0]) * bf2f(pw[g].x & 0xffffu); t[1] += sigmoid_fast(a[1]) * bf2f(pw[g].x >> 16);
;                         t[2] += sigmoid_fast(a[2]) * bf2f(pw[g].y & 0xffffu); t[3] += sigmoid_fast(a[3]) * bf2f(pw[g].y >> 16); }
;                 v2u w; w.x = cvt_pk_bf16(t[0], t[1]); w.y = cvt_pk_bf16(t[2], t[3]);
;                 *(v2u*)(T + (size_t)row * 1024 + oc) = w; }
	v_pk_fma_f32 v[80:81], v[80:81], v[180:181], v[14:15]
	v_pk_fma_f32 v[82:83], v[82:83], v[180:181], v[16:17]
	v_exp_f32_e32 v80, v80
	v_exp_f32_e32 v82, v82
	v_exp_f32_e32 v81, v81
	v_exp_f32_e32 v83, v83
	v_lshlrev_b32_e32 v184, 16, v200
	v_pk_add_f32 v[80:81], v[80:81], v[182:183]
	v_pk_add_f32 v[82:83], v[82:83], v[182:183]
	v_rcp_f32_e32 v80, v80
	v_rcp_f32_e32 v82, v82
	v_rcp_f32_e32 v81, v81
	v_rcp_f32_e32 v83, v83
	v_and_b32_e32 v185, 0xffff0000, v200
	v_lshlrev_b32_e32 v186, 16, v201
	v_and_b32_e32 v187, 0xffff0000, v201
	v_pk_mul_f32 v[80:81], v[80:81], v[184:185]
	v_pk_mul_f32 v[82:83], v[82:83], v[186:187]
	v_pk_fma_f32 v[76:77], v[76:77], v[180:181], v[10:11]
	v_pk_fma_f32 v[78:79], v[78:79], v[180:181], v[12:13]
	v_exp_f32_e32 v76, v76
	v_exp_f32_e32 v78, v78
	v_exp_f32_e32 v77, v77
	v_exp_f32_e32 v79, v79
	v_lshlrev_b32_e32 v184, 16, v202
	v_pk_add_f32 v[76:77], v[76:77], v[182:183]
	v_pk_add_f32 v[78:79], v[78:79], v[182:183]
	v_rcp_f32_e32 v76, v76
	v_rcp_f32_e32 v78, v78
	v_rcp_f32_e32 v77, v77
	v_rcp_f32_e32 v79, v79
	v_and_b32_e32 v185, 0xffff0000, v202
	v_lshlrev_b32_e32 v186, 16, v203
	v_and_b32_e32 v187, 0xffff0000, v203
	v_pk_fma_f32 v[80:81], v[76:77], v[184:185], v[80:81]
	v_pk_fma_f32 v[82:83], v[78:79], v[186:187], v[82:83]
	v_pk_fma_f32 v[72:73], v[72:73], v[180:181], v[6:7]
	v_pk_fma_f32 v[74:75], v[74:75], v[180:181], v[8:9]
	v_exp_f32_e32 v72, v72
	v_exp_f32_e32 v74, v74
	v_exp_f32_e32 v73, v73
	v_exp_f32_e32 v75, v75
	v_lshlrev_b32_e32 v184, 16, v204
	v_pk_add_f32 v[72:73], v[72:73], v[182:183]
	v_pk_add_f32 v[74:75], v[74:75], v[182:183]
	v_rcp_f32_e32 v72, v72
	v_rcp_f32_e32 v74, v74
	v_rcp_f32_e32 v73, v73
	v_rcp_f32_e32 v75, v75
	v_and_b32_e32 v185, 0xffff0000, v204
	v_lshlrev_b32_e32 v186, 16, v205
	v_and_b32_e32 v187, 0xffff0000, v205
	v_pk_fma_f32 v[80:81], v[72:73], v[184:185], v[80:81]
	v_pk_fma_f32 v[82:83], v[74:75], v[186:187], v[82:83]
	v_pk_fma_f32 v[68:69], v[68:69], v[180:181], v[2:3]
	v_pk_fma_f32 v[70:71], v[70:71], v[180:181], v[4:5]
	v_exp_f32_e32 v68, v68
	v_exp_f32_e32 v70, v70
	v_exp_f32_e32 v69, v69
	v_exp_f32_e32 v71, v71
	v_lshlrev_b32_e32 v184, 16, v206
	v_pk_add_f32 v[68:69], v[68:69], v[182:183]
	v_pk_add_f32 v[70:71], v[70:71], v[182:183]
	v_rcp_f32_e32 v68, v68
	v_rcp_f32_e32 v70, v70
	v_rcp_f32_e32 v69, v69
	v_rcp_f32_e32 v71, v71
	v_and_b32_e32 v185, 0xffff0000, v206
	v_lshlrev_b32_e32 v186, 16, v207
	v_and_b32_e32 v187, 0xffff0000, v207
	v_pk_fma_f32 v[80:81], v[68:69], v[184:185], v[80:81]
	v_pk_fma_f32 v[82:83], v[70:71], v[186:187], v[82:83]
	v_cvt_pk_bf16_f32 v18, v80, v81
	v_cvt_pk_bf16_f32 v19, v82, v83
	global_store_dwordx2 v[20:21], v[18:19], off
	s_nop 1
	v_lshl_add_u64 v[20:21], v[20:21], 0, s[2:3]
	s_waitcnt vmcnt(4)
	v_pk_fma_f32 v[64:65], v[64:65], v[180:181], v[14:15]
	v_pk_fma_f32 v[66:67], v[66:67], v[180:181], v[16:17]
	v_exp_f32_e32 v64, v64
	v_exp_f32_e32 v66, v66
	v_exp_f32_e32 v65, v65
	v_exp_f32_e32 v67, v67
	v_lshlrev_b32_e32 v184, 16, v208
	v_pk_add_f32 v[64:65], v[64:65], v[182:183]
	v_pk_add_f32 v[66:67], v[66:67], v[182:183]
	v_rcp_f32_e32 v64, v64
	v_rcp_f32_e32 v66, v66
	v_rcp_f32_e32 v65, v65
	v_rcp_f32_e32 v67, v67
	v_and_b32_e32 v185, 0xffff0000, v208
	v_lshlrev_b32_e32 v186, 16, v209
	v_and_b32_e32 v187, 0xffff0000, v209
	v_pk_mul_f32 v[64:65], v[64:65], v[184:185]
	v_pk_mul_f32 v[66:67], v[66:67], v[186:187]
	v_pk_fma_f32 v[60:61], v[60:61], v[180:181], v[10:11]
	v_pk_fma_f32 v[62:63], v[62:63], v[180:181], v[12:13]
	v_exp_f32_e32 v60, v60
	v_exp_f32_e32 v62, v62
	v_exp_f32_e32 v61, v61
	v_exp_f32_e32 v63, v63
	v_lshlrev_b32_e32 v184, 16, v210
	v_pk_add_f32 v[60:61], v[60:61], v[182:183]
	v_pk_add_f32 v[62:63], v[62:63], v[182:183]
	v_rcp_f32_e32 v60, v60
	v_rcp_f32_e32 v62, v62
	v_rcp_f32_e32 v61, v61
	v_rcp_f32_e32 v63, v63
	v_and_b32_e32 v185, 0xffff0000, v210
	v_lshlrev_b32_e32 v186, 16, v211
	v_and_b32_e32 v187, 0xffff0000, v211
	v_pk_fma_f32 v[64:65], v[60:61], v[184:185], v[64:65]
	v_pk_fma_f32 v[66:67], v[62:63], v[186:187], v[66:67]
	v_pk_fma_f32 v[56:57], v[56:57], v[180:181], v[6:7]
	v_pk_fma_f32 v[58:59], v[58:59], v[180:181], v[8:9]
	v_exp_f32_e32 v56, v56
	v_exp_f32_e32 v58, v58
	v_exp_f32_e32 v57, v57
	v_exp_f32_e32 v59, v59
	v_lshlrev_b32_e32 v184, 16, v212
	v_pk_add_f32 v[56:57], v[56:57], v[182:183]
	v_pk_add_f32 v[58:59], v[58:59], v[182:183]
	v_rcp_f32_e32 v56, v56
	v_rcp_f32_e32 v58, v58
	v_rcp_f32_e32 v57, v57
	v_rcp_f32_e32 v59, v59
	v_and_b32_e32 v185, 0xffff0000, v212
	v_lshlrev_b32_e32 v186, 16, v213
	v_and_b32_e32 v187, 0xffff0000, v213
	v_pk_fma_f32 v[64:65], v[56:57], v[184:185], v[64:65]
	v_pk_fma_f32 v[66:67], v[58:59], v[186:187], v[66:67]
	v_pk_fma_f32 v[52:53], v[52:53], v[180:181], v[2:3]
	v_pk_fma_f32 v[54:55], v[54:55], v[180:181], v[4:5]
	v_exp_f32_e32 v52, v52
	v_exp_f32_e32 v54, v54
	v_exp_f32_e32 v53, v53
	v_exp_f32_e32 v55, v55
	v_lshlrev_b32_e32 v184, 16, v214
	v_pk_add_f32 v[52:53], v[52:53], v[182:183]
	v_pk_add_f32 v[54:55], v[54:55], v[182:183]
	v_rcp_f32_e32 v52, v52
	v_rcp_f32_e32 v54, v54
	v_rcp_f32_e32 v53, v53
	v_rcp_f32_e32 v55, v55
	v_and_b32_e32 v185, 0xffff0000, v214
	v_lshlrev_b32_e32 v186, 16, v215
	v_and_b32_e32 v187, 0xffff0000, v215
	v_pk_fma_f32 v[64:65], v[52:53], v[184:185], v[64:65]
	v_pk_fma_f32 v[66:67], v[54:55], v[186:187], v[66:67]
	v_cvt_pk_bf16_f32 v18, v64, v65
	v_cvt_pk_bf16_f32 v19, v66, v67
	global_store_dwordx2 v[20:21], v[18:19], off
	s_nop 1
	v_lshl_add_u64 v[20:21], v[20:21], 0, s[2:3]
	s_waitcnt vmcnt(0)
; __device__ __forceinline__ float bf2f(unsigned b) { return __uint_as_float(b << 16); }
; __device__ __forceinline__ unsigned cvt_pk_bf16(float lo, float hi) { unsigned r; asm volatile("v_cvt_pk_bf16_f32 %0, %1, %2" : "=v"(r) : "v"(lo), "v"(hi)); return r; }
; __device__ __forceinline__ float sigmoid_fast(float x) { return __builtin_amdgcn_rcpf(1.0f + __expf(-x)); }
;     __device__ __forceinline__ void operator()(EPI_SIG) const {
;     ...
;             for (int m = 0; m < 4; ++m) { const int row = row0 + ai * 128 + m * 16; const bf16* prow = P + (((((size_t)u.pm * 16 + u.pn) * 2 + ai) * 4 + m) * 8 + (wr * 4 + wc)) * 1024 + (fq * 16 + fr) * 4;
;                 v2u pw[4];
; #pragma unroll
;                 for (int g = 0; g < 4; ++g) pw[g] = *(const v2u*)(prow + g * 256);
;                 f32x4 t = (f32x4){0.f, 0.f, 0.f, 0.f};
; #pragma unroll
;                 for (int bj = 0; bj < 2; ++bj)
; #pragma unroll
;                     for (int n = 0; n < 2; ++n) { const int g = 2 * bj + n; const f32x4 a = acc[ai][bj][m][n] + bv[g];
;                         t[0] += sigmoid_fast(a[0]) * bf2f(pw[g].x & 0xffffu); t[1] += sigmoid_fast(a[1]) * bf2f(pw[g].x >> 16);
;                         t[2] += sigmoid_fast(a[2]) * bf2f(pw[g].y & 0xffffu); t[3] += sigmoid_fast(a[3]) * bf2f(pw[g].y >> 16); }
;                 v2u w; w.x = cvt_pk_bf16(t[0], t[1]); w.y = cvt_pk_bf16(t[2], t[3]);
;                 *(v2u*)(T + (size_t)row * 1024 + oc) = w; }
	v_pk_fma_f32 v[46:47], v[46:47], v[180:181], v[14:15]
	v_pk_fma_f32 v[48:49], v[48:49], v[180:181], v[16:17]
	v_exp_f32_e32 v46, v46
	v_exp_f32_e32 v48, v48
	v_exp_f32_e32 v47, v47
	v_exp_f32_e32 v49, v49
	v_lshlrev_b32_e32 v184, 16, v216
	v_pk_add_f32 v[46:47], v[46:47], v[182:183]
	v_pk_add_f32 v[48:49], v[48:49], v[182:183]
	v_rcp_f32_e32 v46, v46
	v_rcp_f32_e32 v48, v48
	v_rcp_f32_e32 v47, v47
	v_rcp_f32_e32 v49, v49
	v_and_b32_e32 v185, 0xffff0000, v216
	v_lshlrev_b32_e32 v186, 16, v217
	v_and_b32_e32 v187, 0xffff0000, v217
	v_pk_mul_f32 v[46:47], v[46:47], v[184:185]
	v_pk_mul_f32 v[48:49], v[48:49], v[186:187]
	v_pk_fma_f32 v[42:43], v[42:43], v[180:181], v[10:11]
	v_pk_fma_f32 v[44:45], v[44:45], v[180:181], v[12:13]
	v_exp_f32_e32 v42, v42
	v_exp_f32_e32 v44, v44
	v_exp_f32_e32 v43, v43
	v_exp_f32_e32 v45, v45
	v_lshlrev_b32_e32 v184, 16, v218
	v_pk_add_f32 v[42:43], v[42:43], v[182:183]
	v_pk_add_f32 v[44:45], v[44:45], v[182:183]
	v_rcp_f32_e32 v42, v42
	v_rcp_f32_e32 v44, v44
	v_rcp_f32_e32 v43, v43
	v_rcp_f32_e32 v45, v45
	v_and_b32_e32 v185, 0xffff0000, v218
	v_lshlrev_b32_e32 v186, 16, v219
	v_and_b32_e32 v187, 0xffff0000, v219
	v_pk_fma_f32 v[46:47], v[42:43], v[184:185], v[46:47]
	v_pk_fma_f32 v[48:49], v[44:45], v[186:187], v[48:49]
	v_pk_fma_f32 v[38:39], v[38:39], v[180:181], v[6:7]
	v_pk_fma_f32 v[40:41], v[40:41], v[180:181], v[8:9]
	v_exp_f32_e32 v38, v38
	v_exp_f32_e32 v40, v40
	v_exp_f32_e32 v39, v39
	v_exp_f32_e32 v41, v41
	v_lshlrev_b32_e32 v184, 16, v220
	v_pk_add_f32 v[38:39], v[38:39], v[182:183]
	v_pk_add_f32 v[40:41], v[40:41], v[182:183]
	v_rcp_f32_e32 v38, v38
	v_rcp_f32_e32 v40, v40
	v_rcp_f32_e32 v39, v39
	v_rcp_f32_e32 v41, v41
	v_and_b32_e32 v185, 0xffff0000, v220
	v_lshlrev_b32_e32 v186, 16, v221
	v_and_b32_e32 v187, 0xffff0000, v221
	v_pk_fma_f32 v[46:47], v[38:39], v[184:185], v[46:47]
	v_pk_fma_f32 v[48:49], v[40:41], v[186:187], v[48:49]
	v_pk_fma_f32 v[34:35], v[34:35], v[180:181], v[2:3]
	v_pk_fma_f32 v[36:37], v[36:37], v[180:181], v[4:5]
	v_exp_f32_e32 v34, v34
	v_exp_f32_e32 v36, v36
	v_exp_f32_e32 v35, v35
	v_exp_f32_e32 v37, v37
	v_lshlrev_b32_e32 v184, 16, v222
	v_pk_add_f32 v[34:35], v[34:35], v[182:183]
	v_pk_add_f32 v[36:37], v[36:37], v[182:183]
	v_rcp_f32_e32 v34, v34
	v_rcp_f32_e32 v36, v36
	v_rcp_f32_e32 v35, v35
	v_rcp_f32_e32 v37, v37
	v_and_b32_e32 v185, 0xffff0000, v222
	v_lshlrev_b32_e32 v186, 16, v223
	v_and_b32_e32 v187, 0xffff0000, v223
	v_pk_fma_f32 v[46:47], v[34:35], v[184:185], v[46:47]
	v_pk_fma_f32 v[48:49], v[36:37], v[186:187], v[48:49]
	v_cvt_pk_bf16_f32 v18, v46, v47
	v_cvt_pk_bf16_f32 v19, v48, v49
	s_mov_b64 s[2:3], -1
	s_andn2_b64 vcc, exec, s[0:1]
	global_store_dwordx2 v[20:21], v[18:19], off
	s_nop 1
	s_cbranch_vccnz .LBB0_1852
	s_andn2_b64 vcc, exec, s[4:5]
	s_cbranch_vccnz .LBB0_1851
	s_barrier
	s_branch .LBB0_1851
